# row-sum butterflies in mix/phase7/final via permlane32/16_swap + DPP adds instead of ds_bpermute (same pairing order)
# speedup vs baseline: 1.0037x; 1.0037x over previous
; __device__ __forceinline__ float bflo(unsigned w) { return __uint_as_float(w << 16); }
; __device__ __forceinline__ float bfhi(unsigned w) { return __uint_as_float(w & 0xFFFF0000u); }
; __device__ __forceinline__ void mix_store(PP p, int r, int c0, const MixRow& m, const f32x4 (&gr)[2], const f32x4 (&ga)[2]) {
;     bf16_t* mix = (bf16_t*)(p->ws + WS_HB);
;     float rn[8], at[8]; float s1 = 0.f, s2 = 0.f;
; #pragma unroll
;     for (int e = 0; e < 8; ++e) {
;         const unsigned wy = m.vy[e >> 1], wf = m.vf[e >> 1], wb = m.vb[e >> 1], wg = m.vg[e >> 1], wa = m.va[e >> 1];
;         const float cfe = e < 4 ? m.cf0[e & 3] : m.cf1[e & 3], cbe = e < 4 ? m.cb0[e & 3] : m.cb1[e & 3];
;         const float y = ((e & 1) ? bfhi(wy) : bflo(wy)) + ((e & 1) ? bfhi(wf) : bflo(wf)) * cfe + ((e & 1) ? bfhi(wb) : bflo(wb)) * cbe;
;         const float xg = (e & 1) ? bfhi(wg) : bflo(wg);
;         rn[e] = gelu_tanh_(xg) * y; s1 += rn[e] * rn[e];
.LBB0_777:
	v_lshl_add_u64 v[18:19], v[74:75], 0, v[54:55]
	v_add_co_u32_e32 v20, vcc, 0x3c77000, v18
	s_waitcnt vmcnt(7)
	v_lshl_add_u64 v[28:29], v[72:73], 0, v[54:55]
	v_addc_co_u32_e32 v21, vcc, 0, v19, vcc
	v_add_co_u32_e32 v22, vcc, 0x5c77000, v18
	v_ashrrev_i32_e32 v16, 6, v52
	s_nop 0
	v_addc_co_u32_e32 v23, vcc, 0, v19, vcc
	global_load_dwordx4 v[32:35], v[28:29], off
	global_load_dwordx4 v[24:27], v[20:21], off
	global_load_dwordx4 v[36:39], v[22:23], off
	v_add_co_u32_e32 v20, vcc, 0x7c77000, v18
	v_ashrrev_i32_e32 v17, 31, v16
	s_nop 0
	v_addc_co_u32_e32 v21, vcc, 0, v19, vcc
	v_lshlrev_b64 v[16:17], 11, v[16:17]
	v_add_co_u32_e32 v18, vcc, 0x1c77000, v18
	v_lshl_add_u64 v[16:17], v[64:65], 0, v[16:17]
	s_nop 0
	v_addc_co_u32_e32 v19, vcc, 0, v19, vcc
	global_load_dwordx4 v[104:107], v[16:17], off
	global_load_dwordx4 v[44:47], v[20:21], off
	global_load_dwordx4 v[28:31], v[18:19], off
	v_add_co_u32_e32 v18, vcc, 0x104000, v16
	v_lshl_add_u64 v[90:91], v[16:17], 0, s[18:19]
	s_nop 0
	v_addc_co_u32_e32 v19, vcc, 0, v17, vcc
	global_load_dwordx4 v[108:111], v[18:19], off
	global_load_dwordx4 v[40:43], v[16:17], off offset:16
	v_add_u32_e32 v18, s26, v52
	v_cmp_gt_i32_e32 vcc, s21, v18
	s_waitcnt vmcnt(7)
	v_and_b32_e32 v53, 0xffff0000, v32
	v_cndmask_b32_e32 v80, v52, v18, vcc
	v_ashrrev_i32_e32 v81, 31, v80
	v_mad_i64_i32 v[18:19], s[4:5], v80, s27, v[70:71]
	v_lshlrev_b64 v[84:85], 10, v[80:81]
	v_lshl_add_u64 v[18:19], v[18:19], 0, v[76:77]
	v_lshl_add_u64 v[92:93], v[56:57], 0, v[84:85]
	v_add_co_u32_e32 v88, vcc, s30, v18
	v_lshl_add_u64 v[94:95], v[58:59], 0, v[84:85]
	s_nop 0
	v_addc_co_u32_e32 v89, vcc, 0, v19, vcc
	global_load_dwordx4 v[16:19], v[92:93], off
	global_load_dwordx4 v[20:23], v[94:95], off
	global_load_dwordx4 v[48:51], v[90:91], off offset:16
	v_lshlrev_b32_e32 v96, 16, v32
	v_mul_f32_e32 v32, 0x3d372713, v53
	v_mul_f32_e32 v32, v32, v53
	v_mul_f32_e32 v83, 0.5, v53
	v_fmac_f32_e32 v53, v32, v53
	v_mul_f32_e32 v32, 0x3f4c422a, v53
	v_mul_f32_e32 v90, 0x3d372713, v96
	s_waitcnt vmcnt(5)
	v_lshlrev_b32_e32 v92, 16, v29
	v_and_b32_e32 v53, 0xffff0000, v29
	v_mul_f32_e32 v29, 0x4038aa3b, v32
	v_mul_f32_e32 v103, v90, v96
	v_and_b32_e32 v90, 0xffff0000, v30
	v_lshlrev_b32_e32 v91, 16, v30
	v_exp_f32_e32 v30, v29
	v_and_b32_e32 v116, 0xffff0000, v36
	v_and_b32_e32 v117, 0xffff0000, v44
	s_waitcnt vmcnt(4)
	v_mov_b32_e32 v115, v108
	v_add_f32_e32 v30, 1.0, v30
	v_rcp_f32_e32 v30, v30
	v_mov_b32_e32 v108, v105
	v_and_b32_e32 v93, 0xffff0000, v24
	v_pk_mul_f32 v[108:109], v[108:109], v[116:117]
	v_fma_f32 v30, v30, -2.0, 1.0
	v_lshlrev_b32_e32 v112, 16, v36
	v_add_f32_e32 v36, v108, v93
	v_add_f32_e32 v30, 1.0, v30
	v_lshlrev_b32_e32 v97, 16, v33
	v_add_f32_e32 v36, v36, v109
	v_mul_f32_e32 v30, v83, v30
	v_mul_f32_e32 v116, v36, v30
	v_mov_b32_e32 v30, v96
	v_mul_f32_e32 v36, 0x3d372713, v97
	v_fmac_f32_e32 v30, v103, v30
	v_mul_f32_e32 v36, v36, v97
	v_mul_f32_e32 v30, 0x3f4c422a, v30
	v_pk_mul_f32 v[108:109], v[96:97], 0.5 op_sel_hi:[1,0]
	v_fmac_f32_e32 v97, v36, v97
	v_mul_f32_e32 v30, 0x4038aa3b, v30
	v_mul_f32_e32 v36, 0x3f4c422a, v97
	v_exp_f32_e32 v30, v30
	v_mul_f32_e32 v36, 0x4038aa3b, v36
	v_exp_f32_e32 v36, v36
	v_mov_b32_e32 v114, v104
	v_add_f32_e32 v30, 1.0, v30
	v_rcp_f32_e32 v96, v30
	v_add_f32_e32 v30, 1.0, v36
	v_rcp_f32_e32 v97, v30
	v_lshlrev_b32_e32 v113, 16, v44
	v_lshlrev_b32_e32 v119, 16, v45
	v_pk_mul_f32 v[104:105], v[114:115], v[112:113]
	v_pk_fma_f32 v[96:97], v[96:97], 2.0, 1.0 op_sel_hi:[1,0,0] neg_lo:[1,0,0] neg_hi:[1,0,0]
	v_lshlrev_b32_e32 v118, 16, v37
	v_pk_add_f32 v[96:97], v[96:97], 1.0 op_sel_hi:[1,0]
	v_mov_b32_e32 v112, v106
	v_pk_mul_f32 v[96:97], v[108:109], v[96:97]
	v_lshlrev_b32_e32 v108, 16, v24
	v_and_b32_e32 v24, 0xffff0000, v33
	v_mul_f32_e32 v33, 0x3d372713, v24
	v_mul_f32_e32 v33, v33, v24
	v_mul_f32_e32 v30, 0.5, v24
	v_fmac_f32_e32 v24, v33, v24
	v_mul_f32_e32 v24, 0x3f4c422a, v24
	v_mul_f32_e32 v24, 0x4038aa3b, v24
	v_exp_f32_e32 v24, v24
	v_mov_b32_e32 v113, v110
	v_pk_mul_f32 v[112:113], v[112:113], v[118:119]
	v_lshlrev_b32_e32 v109, 16, v25
	v_add_f32_e32 v24, 1.0, v24
	v_mov_b32_e32 v114, v104
	v_mov_b32_e32 v115, v112
	v_rcp_f32_e32 v24, v24
	v_pk_add_f32 v[108:109], v[114:115], v[108:109]
	v_mov_b32_e32 v112, v105
	v_pk_add_f32 v[104:105], v[108:109], v[112:113]
	v_fma_f32 v24, v24, -2.0, 1.0
	v_pk_mul_f32 v[96:97], v[104:105], v[96:97]
	v_add_f32_e32 v24, 1.0, v24
	v_pk_mul_f32 v[104:105], v[96:97], v[96:97]
	v_mov_b32_e32 v110, v107
	v_fma_f32 v33, v116, v116, v104
	v_add_f32_e32 v33, v105, v33
	v_mul_f32_e32 v105, v30, v24
	v_and_b32_e32 v30, 0xffff0000, v25
	v_and_b32_e32 v25, 0xffff0000, v45
	v_and_b32_e32 v24, 0xffff0000, v37
	v_pk_mul_f32 v[24:25], v[110:111], v[24:25]
	s_waitcnt vmcnt(3)
	v_mov_b32_e32 v36, v40
	v_add_f32_e32 v24, v24, v30
	v_add_f32_e32 v93, v24, v25
	v_lshlrev_b32_e32 v25, 16, v46
	v_lshlrev_b32_e32 v24, 16, v38
	s_waitcnt vmcnt(0)
; __device__ __forceinline__ float bflo(unsigned w) { return __uint_as_float(w << 16); }
; __device__ __forceinline__ float bfhi(unsigned w) { return __uint_as_float(w & 0xFFFF0000u); }
; __device__ __forceinline__ float wave_sum(float v) {
; #pragma unroll
;     for (int o = 32; o >= 1; o >>= 1) v += __shfl_xor(v, o);
;     return v;
; }
; __device__ __forceinline__ void mix_store(PP p, int r, int c0, const MixRow& m, const f32x4 (&gr)[2], const f32x4 (&ga)[2]) {
;     ...
;     float rn[8], at[8]; float s1 = 0.f, s2 = 0.f;
; #pragma unroll
;     for (int e = 0; e < 8; ++e) {
;         const unsigned wy = m.vy[e >> 1], wf = m.vf[e >> 1], wb = m.vb[e >> 1], wg = m.vg[e >> 1], wa = m.va[e >> 1];
;         const float cfe = e < 4 ? m.cf0[e & 3] : m.cf1[e & 3], cbe = e < 4 ? m.cb0[e & 3] : m.cb1[e & 3];
;         const float y = ((e & 1) ? bfhi(wy) : bflo(wy)) + ((e & 1) ? bfhi(wf) : bflo(wf)) * cfe + ((e & 1) ? bfhi(wb) : bflo(wb)) * cbe;
;         const float xg = (e & 1) ? bfhi(wg) : bflo(wg);
;         rn[e] = gelu_tanh_(xg) * y; s1 += rn[e] * rn[e];
;         at[e] = (e & 1) ? bfhi(wa) : bflo(wa); s2 += at[e] * at[e];
;     }
;     const float r1 = rsqrtf(wave_sum(s1) * (1.0f / 512.0f) + EPS), r2 = rsqrtf(wave_sum(s2) * (1.0f / 512.0f) + EPS);
	v_mov_b32_e32 v37, v48
	v_pk_mul_f32 v[24:25], v[36:37], v[24:25]
	v_lshlrev_b32_e32 v37, 16, v34
	v_mul_f32_e32 v30, 0x3d372713, v37
	v_and_b32_e32 v36, 0xffff0000, v34
	v_mul_f32_e32 v30, v30, v37
	v_mov_b32_e32 v34, v37
	v_fmac_f32_e32 v34, v30, v34
	v_mul_f32_e32 v30, 0x3f4c422a, v34
	v_mul_f32_e32 v34, 0x3d372713, v36
	v_mul_f32_e32 v34, v34, v36
	v_pk_mul_f32 v[44:45], v[36:37], 0.5 op_sel_hi:[1,0]
	v_fmac_f32_e32 v36, v34, v36
	v_mul_f32_e32 v30, 0x4038aa3b, v30
	v_mul_f32_e32 v34, 0x3f4c422a, v36
	v_exp_f32_e32 v30, v30
	v_mul_f32_e32 v34, 0x4038aa3b, v34
	v_exp_f32_e32 v34, v34
	v_and_b32_e32 v37, 0xffff0000, v46
	v_add_f32_e32 v30, 1.0, v30
	v_rcp_f32_e32 v107, v30
	v_add_f32_e32 v30, 1.0, v34
	v_rcp_f32_e32 v106, v30
	v_and_b32_e32 v36, 0xffff0000, v38
	v_mov_b32_e32 v48, v41
	v_pk_mul_f32 v[36:37], v[48:49], v[36:37]
	v_pk_fma_f32 v[40:41], v[106:107], 2.0, 1.0 op_sel_hi:[1,0,0] neg_lo:[1,0,0] neg_hi:[1,0,0]
	v_and_b32_e32 v95, 0xffff0000, v28
	v_pk_add_f32 v[40:41], v[40:41], 1.0 op_sel_hi:[1,0]
	v_mov_b32_e32 v48, v36
	v_pk_mul_f32 v[40:41], v[44:45], v[40:41]
	v_and_b32_e32 v44, 0xffff0000, v26
	v_lshlrev_b32_e32 v45, 16, v26
	v_mov_b32_e32 v49, v24
	v_lshlrev_b32_e32 v94, 16, v28
	v_mul_f32_e32 v28, v95, v95
	v_pk_add_f32 v[44:45], v[48:49], v[44:45]
	v_mov_b32_e32 v24, v37
	v_mov_b32_e32 v104, v92
	v_pk_fma_f32 v[28:29], v[94:95], v[94:95], v[28:29] op_sel_hi:[1,1,0]
	v_pk_add_f32 v[24:25], v[44:45], v[24:25]
	v_pk_mul_f32 v[108:109], v[92:93], v[104:105]
	v_pk_mul_f32 v[106:107], v[24:25], v[40:41]
	v_pk_fma_f32 v[28:29], v[92:93], v[104:105], v[28:29]
	v_pk_mul_f32 v[36:37], v[108:109], v[108:109]
	v_mul_f32_e32 v32, v53, v53
	v_pk_mul_f32 v[120:121], v[90:91], v[90:91]
	v_pk_mul_f32 v[24:25], v[106:107], v[106:107]
	v_mov_b32_e32 v29, v37
	v_pk_add_f32 v[28:29], v[28:29], v[32:33]
	v_mov_b32_e32 v32, v121
	v_mov_b32_e32 v33, v25
	v_pk_add_f32 v[28:29], v[32:33], v[28:29]
	v_lshlrev_b32_e32 v33, 16, v47
	v_lshlrev_b32_e32 v32, 16, v39
	v_mov_b32_e32 v36, v42
	v_mov_b32_e32 v37, v50
	v_pk_mul_f32 v[32:33], v[36:37], v[32:33]
	v_and_b32_e32 v36, 0xffff0000, v39
	v_lshlrev_b32_e32 v39, 16, v35
	v_mul_f32_e32 v25, 0x3d372713, v39
	v_mul_f32_e32 v25, v25, v39
	v_mov_b32_e32 v26, v39
	v_fmac_f32_e32 v26, v25, v26
	v_mul_f32_e32 v25, 0x3f4c422a, v26
	v_mul_f32_e32 v25, 0x4038aa3b, v25
	v_exp_f32_e32 v25, v25
	v_and_b32_e32 v38, 0xffff0000, v35
	v_mov_b32_e32 v30, v38
	v_and_b32_e32 v37, 0xffff0000, v47
	v_add_f32_e32 v25, 1.0, v25
	v_rcp_f32_e32 v35, v25
	v_mul_f32_e32 v25, 0x3d372713, v38
	v_mul_f32_e32 v25, v25, v38
	v_fmac_f32_e32 v30, v25, v30
	v_mul_f32_e32 v25, 0x3f4c422a, v30
	v_mul_f32_e32 v25, 0x4038aa3b, v25
	v_exp_f32_e32 v25, v25
	v_mov_b32_e32 v50, v43
	v_pk_mul_f32 v[36:37], v[50:51], v[36:37]
	v_and_b32_e32 v26, 0xffff0000, v27
	v_add_f32_e32 v25, 1.0, v25
	v_rcp_f32_e32 v34, v25
	v_lshlrev_b32_e32 v27, 16, v27
	v_mov_b32_e32 v40, v36
	v_mov_b32_e32 v41, v32
	v_pk_add_f32 v[26:27], v[40:41], v[26:27]
	v_mov_b32_e32 v32, v37
	v_pk_add_f32 v[26:27], v[26:27], v[32:33]
	v_pk_fma_f32 v[32:33], v[34:35], 2.0, 1.0 op_sel_hi:[1,0,0] neg_lo:[1,0,0] neg_hi:[1,0,0]
	v_pk_mul_f32 v[34:35], v[38:39], 0.5 op_sel_hi:[1,0]
	v_pk_add_f32 v[32:33], v[32:33], 1.0 op_sel_hi:[1,0]
	v_and_b32_e32 v110, 0xffff0000, v31
	v_pk_mul_f32 v[32:33], v[34:35], v[32:33]
	v_lshlrev_b32_e32 v111, 16, v31
	v_pk_mul_f32 v[104:105], v[26:27], v[32:33]
	v_pk_mul_f32 v[30:31], v[110:111], v[110:111]
	v_pk_mul_f32 v[26:27], v[104:105], v[104:105]
	v_mov_b32_e32 v121, v24
	v_pk_add_f32 v[24:25], v[120:121], v[28:29]
	v_mov_b32_e32 v28, v31
	v_mov_b32_e32 v29, v27
	v_pk_add_f32 v[24:25], v[28:29], v[24:25]
	v_mov_b32_e32 v31, v26
	v_pk_add_f32 v[24:25], v[30:31], v[24:25]
	v_ashrrev_i32_e32 v82, 6, v80
	v_ashrrev_i32_e32 v83, 31, v82
	v_lshl_add_u64 v[86:87], v[60:61], 0, v[84:85]
	v_lshl_add_u64 v[36:37], v[62:63], 0, v[84:85]
	s_waitcnt lgkmcnt(0)
	v_mov_b32_e32 v27, v25
	v_mov_b32_e32 v26, v24
	s_nop 1
	v_permlane32_swap_b32_e32 v25, v27
	v_permlane32_swap_b32_e32 v24, v26
	v_pk_add_f32 v[40:41], v[24:25], v[26:27]
	v_lshlrev_b64 v[38:39], 11, v[82:83]
	global_load_dwordx4 v[32:35], v[86:87], off
	global_load_dwordx4 v[28:31], v[88:89], off offset:1024
	v_lshl_add_u64 v[82:83], v[64:65], 0, v[38:39]
	global_load_dwordx4 v[24:27], v[36:37], off
	global_load_dwordx4 v[44:47], v[82:83], off
	s_waitcnt lgkmcnt(0)
	v_mov_b32_e32 v43, v41
	v_mov_b32_e32 v42, v40
	s_nop 1
	v_permlane16_swap_b32_e32 v41, v43
	v_permlane16_swap_b32_e32 v40, v42
	v_pk_add_f32 v[36:37], v[40:41], v[42:43]
	v_add_co_u32_e32 v86, vcc, s9, v82
	v_lshl_add_u64 v[84:85], v[82:83], 0, s[18:19]
	s_nop 0
	v_addc_co_u32_e32 v87, vcc, 0, v83, vcc
	s_waitcnt lgkmcnt(0)
	s_nop 1
	v_add_f32_dpp v88, v36, v36 row_ror:8 row_mask:0xf bank_mask:0xf
	v_add_f32_dpp v89, v37, v37 row_ror:8 row_mask:0xf bank_mask:0xf
	global_load_dwordx4 v[48:51], v[86:87], off
	global_load_dwordx4 v[36:39], v[82:83], off offset:16
	global_load_dwordx4 v[40:43], v[84:85], off offset:16
	s_waitcnt lgkmcnt(0)
	s_nop 1
	v_add_f32_dpp v82, v88, v88 row_ror:4 row_mask:0xf bank_mask:0xf
	v_add_f32_dpp v83, v89, v89 row_ror:4 row_mask:0xf bank_mask:0xf
	s_waitcnt lgkmcnt(0)
	s_nop 1
	v_add_f32_dpp v82, v82, v82 quad_perm:[2,3,0,1] row_mask:0xf bank_mask:0xf
	v_add_f32_dpp v83, v83, v83 quad_perm:[2,3,0,1] row_mask:0xf bank_mask:0xf
	s_waitcnt lgkmcnt(0)
; __device__ __forceinline__ unsigned pk2(float lo, float hi) { unsigned r; asm("v_cvt_pk_bf16_f32 %0, %1, %2" : "=v"(r) : "v"(lo), "v"(hi)); return r; }
; __device__ __forceinline__ float bflo(unsigned w) { return __uint_as_float(w << 16); }
; __device__ __forceinline__ float bfhi(unsigned w) { return __uint_as_float(w & 0xFFFF0000u); }
; __device__ __forceinline__ void mix_store(PP p, int r, int c0, const MixRow& m, const f32x4 (&gr)[2], const f32x4 (&ga)[2]) {
;     ...
;     float rn[8], at[8]; float s1 = 0.f, s2 = 0.f;
; #pragma unroll
;     for (int e = 0; e < 8; ++e) {
;         const unsigned wy = m.vy[e >> 1], wf = m.vf[e >> 1], wb = m.vb[e >> 1], wg = m.vg[e >> 1], wa = m.va[e >> 1];
;         const float cfe = e < 4 ? m.cf0[e & 3] : m.cf1[e & 3], cbe = e < 4 ? m.cb0[e & 3] : m.cb1[e & 3];
;         const float y = ((e & 1) ? bfhi(wy) : bflo(wy)) + ((e & 1) ? bfhi(wf) : bflo(wf)) * cfe + ((e & 1) ? bfhi(wb) : bflo(wb)) * cbe;
;         const float xg = (e & 1) ? bfhi(wg) : bflo(wg);
;         rn[e] = gelu_tanh_(xg) * y; s1 += rn[e] * rn[e];
;     ...
;     const float r1 = rsqrtf(wave_sum(s1) * (1.0f / 512.0f) + EPS), r2 = rsqrtf(wave_sum(s2) * (1.0f / 512.0f) + EPS);
;     u32x4 o1, o2;
; #pragma unroll
;     for (int e2 = 0; e2 < 4; ++e2) {
;         o1[e2] = pk2(rn[2 * e2] * r1 * gr[e2 >> 1][(2 * e2) & 3], rn[2 * e2 + 1] * r1 * gr[e2 >> 1][(2 * e2 + 1) & 3]);
;         o2[e2] = pk2(at[2 * e2] * r2 * ga[e2 >> 1][(2 * e2) & 3], at[2 * e2 + 1] * r2 * ga[e2 >> 1][(2 * e2 + 1) & 3]);
;     }
;     *(u32x4*)(mix + (size_t)r * D + c0) = o1; *(u32x4*)(mix + (size_t)r * D + 512 + c0) = o2;
	s_nop 1
	v_add_f32_dpp v82, v82, v82 quad_perm:[1,0,3,2] row_mask:0xf bank_mask:0xf
	v_add_f32_dpp v83, v83, v83 quad_perm:[1,0,3,2] row_mask:0xf bank_mask:0xf
	s_nop 0
	v_pk_fma_f32 v[82:83], v[82:83], s[20:21], v[78:79] op_sel_hi:[1,0,0]
	s_nop 0
	v_mul_f32_e32 v84, 0x4b800000, v83
	v_cmp_gt_f32_e32 vcc, s31, v83
	v_cmp_gt_f32_e64 s[4:5], s31, v82
	s_nop 0
	v_cndmask_b32_e32 v83, v83, v84, vcc
	v_mul_f32_e32 v84, 0x4b800000, v82
	v_rsq_f32_e32 v83, v83
	v_cndmask_b32_e64 v82, v82, v84, s[4:5]
	v_rsq_f32_e32 v82, v82
	v_mul_f32_e32 v84, 0x45800000, v83
	v_cndmask_b32_e32 v85, v83, v84, vcc
	v_mul_f32_e32 v83, 0x45800000, v82
	v_cndmask_b32_e64 v89, v82, v83, s[4:5]
	v_mul_f32_e32 v82, v96, v85
	v_mul_f32_e32 v83, v116, v85
	v_mul_f32_e32 v82, v4, v82
	v_mul_f32_e32 v83, v5, v83
	v_cvt_pk_bf16_f32 v82, v82, v83
	v_mul_f32_e32 v83, v89, v94
	v_mul_f32_e32 v84, v89, v95
	v_mul_f32_e32 v83, v0, v83
	v_mul_f32_e32 v84, v1, v84
	v_cvt_pk_bf16_f32 v86, v83, v84
	v_mul_f32_e32 v83, v97, v85
	v_mul_f32_e32 v84, v109, v85
	v_mul_f32_e32 v83, v6, v83
	v_mul_f32_e32 v84, v7, v84
	v_cvt_pk_bf16_f32 v83, v83, v84
	v_mul_f32_e32 v84, v89, v92
	v_mul_f32_e32 v53, v89, v53
	v_mul_f32_e32 v84, v2, v84
	v_mul_f32_e32 v53, v3, v53
	v_cvt_pk_bf16_f32 v87, v84, v53
	v_mul_f32_e32 v53, v107, v85
	v_mul_f32_e32 v84, v106, v85
	v_mul_f32_e32 v53, v12, v53
	v_mul_f32_e32 v84, v13, v84
	v_cvt_pk_bf16_f32 v84, v53, v84
	v_mul_f32_e32 v53, v89, v91
	v_mul_f32_e32 v88, v89, v90
	v_mul_f32_e32 v53, v8, v53
	v_mul_f32_e32 v88, v9, v88
	v_cvt_pk_bf16_f32 v88, v53, v88
	v_mul_f32_e32 v53, v105, v85
	v_mul_f32_e32 v85, v104, v85
	v_lshl_add_u64 v[90:91], v[68:69], 0, v[54:55]
	v_mul_f32_e32 v53, v14, v53
	v_mul_f32_e32 v85, v15, v85
	v_add_co_u32_e32 v90, vcc, 0x10e37000, v90
	v_cvt_pk_bf16_f32 v85, v53, v85
	v_mul_f32_e32 v53, v89, v111
	v_mul_f32_e32 v89, v89, v110
	v_addc_co_u32_e32 v91, vcc, 0, v91, vcc
	v_mul_f32_e32 v89, v11, v89
	v_cmp_ne_u32_e32 vcc, v52, v80
	v_mul_f32_e32 v53, v10, v53
	v_cvt_pk_bf16_f32 v89, v53, v89
	global_store_dwordx4 v[90:91], v[82:85], off
	global_store_dwordx4 v[90:91], v[86:89], off offset:1024
	s_and_saveexec_b64 s[28:29], vcc
	s_cbranch_execz .LBB0_776
	s_waitcnt vmcnt(6)
	v_and_b32_e32 v85, 0xffff0000, v24
	v_lshlrev_b32_e32 v84, 16, v24
	v_mul_f32_e32 v24, v85, v85
	v_pk_fma_f32 v[88:89], v[84:85], v[84:85], v[24:25] op_sel_hi:[1,1,0]
	v_lshlrev_b32_e32 v82, 16, v25
	v_and_b32_e32 v53, 0xffff0000, v25
	v_and_b32_e32 v24, 0xffff0000, v26
	v_lshlrev_b32_e32 v25, 16, v26
	v_and_b32_e32 v26, 0xffff0000, v28
	v_mul_f32_e32 v86, 0x3d372713, v26
	v_mul_f32_e32 v86, v86, v26
	v_mul_f32_e32 v83, 0.5, v26
	v_fmac_f32_e32 v26, v86, v26
	v_mul_f32_e32 v26, 0x3f4c422a, v26
	v_mul_f32_e32 v26, 0x4038aa3b, v26
	v_exp_f32_e32 v26, v26
	v_lshlrev_b32_e32 v93, 16, v32
	v_lshlrev_b32_e32 v92, 16, v20
	s_waitcnt vmcnt(5)
	v_mov_b32_e32 v94, v44
	v_add_f32_e32 v26, 1.0, v26
	v_rcp_f32_e32 v26, v26
	s_waitcnt vmcnt(4)
	v_mov_b32_e32 v95, v48
	v_pk_mul_f32 v[92:93], v[94:95], v[92:93]
	v_and_b32_e32 v95, 0xffff0000, v32
	v_fma_f32 v26, v26, -2.0, 1.0
	v_add_f32_e32 v26, 1.0, v26
	v_and_b32_e32 v94, 0xffff0000, v20
	v_mov_b32_e32 v48, v45
	v_mul_f32_e32 v26, v83, v26
	v_and_b32_e32 v83, 0xffff0000, v16
	v_pk_mul_f32 v[44:45], v[48:49], v[94:95]
	v_lshlrev_b32_e32 v48, 16, v28
	v_add_f32_e32 v20, v44, v83
	v_add_f32_e32 v20, v20, v45
	v_mul_f32_e32 v103, v20, v26
	v_mul_f32_e32 v20, 0x3d372713, v48
	v_mul_f32_e32 v20, v20, v48
	v_mov_b32_e32 v26, v48
	v_lshlrev_b32_e32 v49, 16, v29
	v_fmac_f32_e32 v26, v20, v26
	v_mul_f32_e32 v20, 0x3f4c422a, v26
	v_mul_f32_e32 v26, 0x3d372713, v49
	v_mul_f32_e32 v26, v26, v49
	v_pk_mul_f32 v[94:95], v[48:49], 0.5 op_sel_hi:[1,0]
	v_fmac_f32_e32 v49, v26, v49
	v_mul_f32_e32 v20, 0x4038aa3b, v20
	v_mul_f32_e32 v26, 0x3f4c422a, v49
	v_exp_f32_e32 v20, v20
	v_mul_f32_e32 v26, 0x4038aa3b, v26
	v_exp_f32_e32 v26, v26
	v_lshlrev_b32_e32 v45, 16, v33
	v_add_f32_e32 v20, 1.0, v20
	v_rcp_f32_e32 v48, v20
	v_add_f32_e32 v20, 1.0, v26
	v_rcp_f32_e32 v49, v20
	v_lshlrev_b32_e32 v44, 16, v21
	v_mov_b32_e32 v96, v46
	v_mov_b32_e32 v97, v50
	v_pk_fma_f32 v[48:49], v[48:49], 2.0, 1.0 op_sel_hi:[1,0,0] neg_lo:[1,0,0] neg_hi:[1,0,0]
	v_pk_mul_f32 v[44:45], v[96:97], v[44:45]
	v_pk_add_f32 v[48:49], v[48:49], 1.0 op_sel_hi:[1,0]
	v_mov_b32_e32 v96, v92
	v_pk_mul_f32 v[48:49], v[94:95], v[48:49]
	v_lshlrev_b32_e32 v94, 16, v16
	v_and_b32_e32 v16, 0xffff0000, v29
	v_mul_f32_e32 v26, 0x3d372713, v16
	v_mul_f32_e32 v26, v26, v16
	v_mul_f32_e32 v20, 0.5, v16
	v_fmac_f32_e32 v16, v26, v16
	v_mul_f32_e32 v16, 0x3f4c422a, v16
	v_mul_f32_e32 v16, 0x4038aa3b, v16
	v_exp_f32_e32 v16, v16
	v_lshlrev_b32_e32 v95, 16, v17
	v_mov_b32_e32 v97, v44
	v_pk_add_f32 v[94:95], v[96:97], v[94:95]
	v_add_f32_e32 v16, 1.0, v16
	v_rcp_f32_e32 v16, v16
	v_mov_b32_e32 v44, v93
	v_pk_add_f32 v[28:29], v[94:95], v[44:45]
	v_mov_b32_e32 v50, v47
	v_pk_mul_f32 v[28:29], v[28:29], v[48:49]
	v_fma_f32 v16, v16, -2.0, 1.0
	v_pk_mul_f32 v[44:45], v[28:29], v[28:29]
	v_add_f32_e32 v16, 1.0, v16
	v_fma_f32 v26, v103, v103, v44
	v_add_f32_e32 v91, v45, v26
	v_mul_f32_e32 v45, v20, v16
	v_and_b32_e32 v20, 0xffff0000, v17
	v_and_b32_e32 v17, 0xffff0000, v33
	v_and_b32_e32 v16, 0xffff0000, v21
	v_pk_mul_f32 v[16:17], v[50:51], v[16:17]
	s_waitcnt vmcnt(2)
; __device__ __forceinline__ unsigned pk2(float lo, float hi) { unsigned r; asm("v_cvt_pk_bf16_f32 %0, %1, %2" : "=v"(r) : "v"(lo), "v"(hi)); return r; }
; __device__ __forceinline__ float bflo(unsigned w) { return __uint_as_float(w << 16); }
; __device__ __forceinline__ float bfhi(unsigned w) { return __uint_as_float(w & 0xFFFF0000u); }
; __device__ __forceinline__ void mix_store(PP p, int r, int c0, const MixRow& m, const f32x4 (&gr)[2], const f32x4 (&ga)[2]) {
;     ...
;     float rn[8], at[8]; float s1 = 0.f, s2 = 0.f;
; #pragma unroll
;     for (int e = 0; e < 8; ++e) {
;         const unsigned wy = m.vy[e >> 1], wf = m.vf[e >> 1], wb = m.vb[e >> 1], wg = m.vg[e >> 1], wa = m.va[e >> 1];
;         const float cfe = e < 4 ? m.cf0[e & 3] : m.cf1[e & 3], cbe = e < 4 ? m.cb0[e & 3] : m.cb1[e & 3];
;         const float y = ((e & 1) ? bfhi(wy) : bflo(wy)) + ((e & 1) ? bfhi(wf) : bflo(wf)) * cfe + ((e & 1) ? bfhi(wb) : bflo(wb)) * cbe;
;         const float xg = (e & 1) ? bfhi(wg) : bflo(wg);
;         rn[e] = gelu_tanh_(xg) * y; s1 += rn[e] * rn[e];
;         at[e] = (e & 1) ? bfhi(wa) : bflo(wa); s2 += at[e] * at[e];
;     }
;     const float r1 = rsqrtf(wave_sum(s1) * (1.0f / 512.0f) + EPS), r2 = rsqrtf(wave_sum(s2) * (1.0f / 512.0f) + EPS);
;     u32x4 o1, o2;
; #pragma unroll
;     for (int e2 = 0; e2 < 4; ++e2) {
;         o1[e2] = pk2(rn[2 * e2] * r1 * gr[e2 >> 1][(2 * e2) & 3], rn[2 * e2 + 1] * r1 * gr[e2 >> 1][(2 * e2 + 1) & 3]);
;         o2[e2] = pk2(at[2 * e2] * r2 * ga[e2 >> 1][(2 * e2) & 3], at[2 * e2 + 1] * r2 * ga[e2 >> 1][(2 * e2 + 1) & 3]);
;     }
;     *(u32x4*)(mix + (size_t)r * D + c0) = o1; *(u32x4*)(mix + (size_t)r * D + 512 + c0) = o2;
	v_mov_b32_e32 v21, v40
	v_add_f32_e32 v16, v16, v20
	v_add_f32_e32 v83, v16, v17
	v_lshlrev_b32_e32 v17, 16, v34
	v_lshlrev_b32_e32 v16, 16, v22
	v_mov_b32_e32 v20, v36
	v_pk_mul_f32 v[16:17], v[20:21], v[16:17]
	v_lshlrev_b32_e32 v21, 16, v30
	v_and_b32_e32 v20, 0xffff0000, v30
	v_mul_f32_e32 v26, 0x3d372713, v21
	v_mul_f32_e32 v26, v26, v21
	v_mov_b32_e32 v30, v21
	v_pk_mul_f32 v[32:33], v[20:21], 0.5 op_sel_hi:[1,0]
	v_mul_f32_e32 v21, 0x3d372713, v20
	v_mul_f32_e32 v21, v21, v20
	v_fmac_f32_e32 v30, v26, v30
	v_fmac_f32_e32 v20, v21, v20
	v_mul_f32_e32 v26, 0x3f4c422a, v30
	v_mul_f32_e32 v20, 0x3f4c422a, v20
	v_mul_f32_e32 v26, 0x4038aa3b, v26
	v_mul_f32_e32 v20, 0x4038aa3b, v20
	v_exp_f32_e32 v26, v26
	v_exp_f32_e32 v20, v20
	v_and_b32_e32 v21, 0xffff0000, v34
	v_mov_b32_e32 v40, v37
	v_add_f32_e32 v26, 1.0, v26
	v_add_f32_e32 v20, 1.0, v20
	v_rcp_f32_e32 v47, v26
	v_rcp_f32_e32 v46, v20
	v_and_b32_e32 v20, 0xffff0000, v22
	v_pk_mul_f32 v[20:21], v[40:41], v[20:21]
	v_mov_b32_e32 v41, v16
	v_pk_fma_f32 v[36:37], v[46:47], 2.0, 1.0 op_sel_hi:[1,0,0] neg_lo:[1,0,0] neg_hi:[1,0,0]
	v_mov_b32_e32 v40, v20
	v_pk_add_f32 v[36:37], v[36:37], 1.0 op_sel_hi:[1,0]
	v_mov_b32_e32 v16, v21
	v_pk_mul_f32 v[32:33], v[32:33], v[36:37]
	v_and_b32_e32 v36, 0xffff0000, v18
	v_lshlrev_b32_e32 v37, 16, v18
	v_pk_add_f32 v[36:37], v[40:41], v[36:37]
	v_mov_b32_e32 v44, v82
	v_pk_add_f32 v[16:17], v[36:37], v[16:17]
	v_pk_mul_f32 v[20:21], v[82:83], v[44:45]
	v_pk_mul_f32 v[32:33], v[16:17], v[32:33]
	v_pk_fma_f32 v[36:37], v[82:83], v[44:45], v[88:89]
	v_pk_mul_f32 v[40:41], v[20:21], v[20:21]
	v_mul_f32_e32 v90, v53, v53
	v_pk_mul_f32 v[86:87], v[24:25], v[24:25]
	v_pk_mul_f32 v[16:17], v[32:33], v[32:33]
	v_mov_b32_e32 v37, v41
	v_pk_add_f32 v[36:37], v[36:37], v[90:91]
	v_mov_b32_e32 v40, v87
	v_mov_b32_e32 v41, v17
	v_pk_add_f32 v[36:37], v[40:41], v[36:37]
	v_lshlrev_b32_e32 v40, 16, v23
	v_and_b32_e32 v34, 0xffff0000, v23
	v_lshlrev_b32_e32 v23, 16, v31
	v_mul_f32_e32 v17, 0x3d372713, v23
	v_mul_f32_e32 v17, v17, v23
	v_mov_b32_e32 v18, v23
	v_fmac_f32_e32 v18, v17, v18
	v_mul_f32_e32 v17, 0x3f4c422a, v18
	v_mul_f32_e32 v17, 0x4038aa3b, v17
	v_exp_f32_e32 v17, v17
	v_and_b32_e32 v22, 0xffff0000, v31
	v_mov_b32_e32 v20, v22
	v_lshlrev_b32_e32 v41, 16, v35
	v_add_f32_e32 v17, 1.0, v17
	v_rcp_f32_e32 v31, v17
	v_mul_f32_e32 v17, 0x3d372713, v22
	v_mul_f32_e32 v17, v17, v22
	v_fmac_f32_e32 v20, v17, v20
	v_mul_f32_e32 v17, 0x3f4c422a, v20
	v_mul_f32_e32 v17, 0x4038aa3b, v17
	v_exp_f32_e32 v17, v17
	v_mov_b32_e32 v44, v38
	v_mov_b32_e32 v45, v42
	v_and_b32_e32 v35, 0xffff0000, v35
	v_add_f32_e32 v17, 1.0, v17
	v_rcp_f32_e32 v30, v17
	v_mov_b32_e32 v42, v39
	v_pk_mul_f32 v[40:41], v[44:45], v[40:41]
	v_pk_mul_f32 v[34:35], v[42:43], v[34:35]
	v_and_b32_e32 v18, 0xffff0000, v19
	v_lshlrev_b32_e32 v19, 16, v19
	v_mov_b32_e32 v38, v34
	v_mov_b32_e32 v39, v40
	v_pk_fma_f32 v[30:31], v[30:31], 2.0, 1.0 op_sel_hi:[1,0,0] neg_lo:[1,0,0] neg_hi:[1,0,0]
	v_pk_add_f32 v[18:19], v[38:39], v[18:19]
	v_mov_b32_e32 v40, v35
	v_pk_mul_f32 v[22:23], v[22:23], 0.5 op_sel_hi:[1,0]
	v_pk_add_f32 v[30:31], v[30:31], 1.0 op_sel_hi:[1,0]
	v_pk_add_f32 v[18:19], v[18:19], v[40:41]
	v_pk_mul_f32 v[22:23], v[22:23], v[30:31]
	v_and_b32_e32 v26, 0xffff0000, v27
	v_pk_mul_f32 v[30:31], v[18:19], v[22:23]
	v_lshlrev_b32_e32 v27, 16, v27
	v_pk_mul_f32 v[18:19], v[30:31], v[30:31]
	v_pk_mul_f32 v[22:23], v[26:27], v[26:27]
	v_mov_b32_e32 v87, v16
	v_pk_add_f32 v[16:17], v[86:87], v[36:37]
	v_mov_b32_e32 v34, v23
	v_mov_b32_e32 v35, v19
	v_pk_add_f32 v[16:17], v[34:35], v[16:17]
	v_mov_b32_e32 v23, v18
	v_pk_add_f32 v[16:17], v[22:23], v[16:17]
	s_waitcnt lgkmcnt(0)
	v_mov_b32_e32 v19, v17
	v_mov_b32_e32 v18, v16
	s_nop 1
	v_permlane32_swap_b32_e32 v17, v19
	v_permlane32_swap_b32_e32 v16, v18
	v_pk_add_f32 v[16:17], v[16:17], v[18:19]
	s_waitcnt lgkmcnt(0)
	v_mov_b32_e32 v19, v17
	v_mov_b32_e32 v18, v16
	s_nop 1
	v_permlane16_swap_b32_e32 v17, v19
	v_permlane16_swap_b32_e32 v16, v18
	v_pk_add_f32 v[16:17], v[16:17], v[18:19]
	s_waitcnt lgkmcnt(0)
	s_nop 1
	v_add_f32_dpp v16, v16, v16 row_ror:8 row_mask:0xf bank_mask:0xf
	v_add_f32_dpp v17, v17, v17 row_ror:8 row_mask:0xf bank_mask:0xf
	s_waitcnt lgkmcnt(0)
	s_nop 1
	v_add_f32_dpp v16, v16, v16 row_ror:4 row_mask:0xf bank_mask:0xf
	v_add_f32_dpp v17, v17, v17 row_ror:4 row_mask:0xf bank_mask:0xf
	s_waitcnt lgkmcnt(0)
	s_nop 1
	v_add_f32_dpp v16, v16, v16 quad_perm:[2,3,0,1] row_mask:0xf bank_mask:0xf
	v_add_f32_dpp v17, v17, v17 quad_perm:[2,3,0,1] row_mask:0xf bank_mask:0xf
	s_waitcnt lgkmcnt(0)
	s_nop 1
	v_add_f32_dpp v16, v16, v16 quad_perm:[1,0,3,2] row_mask:0xf bank_mask:0xf
	v_add_f32_dpp v17, v17, v17 quad_perm:[1,0,3,2] row_mask:0xf bank_mask:0xf
	s_nop 0
	v_pk_fma_f32 v[16:17], v[16:17], s[20:21], v[78:79] op_sel_hi:[1,0,0]
	s_nop 0
	v_mul_f32_e32 v18, 0x4b800000, v17
	v_cmp_gt_f32_e32 vcc, s31, v17
	v_cmp_gt_f32_e64 s[4:5], s31, v16
	s_nop 0
	v_cndmask_b32_e32 v17, v17, v18, vcc
	v_mul_f32_e32 v18, 0x4b800000, v16
	v_rsq_f32_e32 v17, v17
	v_cndmask_b32_e64 v16, v16, v18, s[4:5]
	v_rsq_f32_e32 v16, v16
	v_mul_f32_e32 v18, 0x45800000, v17
	v_cndmask_b32_e32 v19, v17, v18, vcc
	v_mul_f32_e32 v17, 0x45800000, v16
	v_cndmask_b32_e64 v23, v16, v17, s[4:5]
	v_mul_f32_e32 v16, v28, v19
	v_mul_f32_e32 v17, v103, v19
	v_mul_f32_e32 v16, v4, v16
	v_mul_f32_e32 v17, v5, v17
	v_cvt_pk_bf16_f32 v16, v16, v17
	v_mul_f32_e32 v17, v23, v84
	v_mul_f32_e32 v18, v23, v85
	v_mul_f32_e32 v17, v0, v17
	v_mul_f32_e32 v18, v1, v18
	v_cvt_pk_bf16_f32 v20, v17, v18
	v_mul_f32_e32 v17, v29, v19
	v_mul_f32_e32 v18, v21, v19
	v_mul_f32_e32 v17, v6, v17
	v_mul_f32_e32 v18, v7, v18
	v_cvt_pk_bf16_f32 v17, v17, v18
	v_mul_f32_e32 v18, v23, v82
	v_mul_f32_e32 v21, v23, v53
	v_mul_f32_e32 v18, v2, v18
	v_mul_f32_e32 v21, v3, v21
	v_cvt_pk_bf16_f32 v21, v18, v21
	v_mul_f32_e32 v18, v33, v19
	v_mul_f32_e32 v22, v32, v19
	v_mul_f32_e32 v18, v12, v18
	v_mul_f32_e32 v22, v13, v22
	v_cvt_pk_bf16_f32 v18, v18, v22
	v_mul_f32_e32 v22, v23, v25
	v_mul_f32_e32 v24, v23, v24
	v_mul_f32_e32 v22, v8, v22
	v_mul_f32_e32 v24, v9, v24
	v_cvt_pk_bf16_f32 v22, v22, v24
	v_mul_f32_e32 v24, v31, v19
	v_mul_f32_e32 v19, v30, v19
	v_mul_f32_e32 v24, v14, v24
	v_mul_f32_e32 v19, v15, v19
	v_cvt_pk_bf16_f32 v19, v24, v19
	v_mul_f32_e32 v24, v23, v27
	v_mul_f32_e32 v23, v23, v26
	v_mul_f32_e32 v24, v10, v24
	v_mul_f32_e32 v23, v11, v23
	v_cvt_pk_bf16_f32 v23, v24, v23
	v_lshlrev_b64 v[24:25], 11, v[80:81]
	v_lshl_add_u64 v[24:25], v[66:67], 0, v[24:25]
	global_store_dwordx4 v[24:25], v[16:19], off
	global_store_dwordx4 v[24:25], v[20:23], off offset:1024
	s_branch .LBB0_776

; __device__ __forceinline__ float bflo(unsigned w) { return __uint_as_float(w << 16); }
; __device__ __forceinline__ float bfhi(unsigned w) { return __uint_as_float(w & 0xFFFF0000u); }
; __device__ __forceinline__ float row_rstd(const f32x4 (&v)[4]) {
;     float ss = 0.f;
; #pragma unroll
;     for (int j = 0; j < 4; ++j) ss += v[j][0] * v[j][0] + v[j][1] * v[j][1] + v[j][2] * v[j][2] + v[j][3] * v[j][3];
;     return rsqrtf(wave_sum(ss) * (1.0f / D) + EPS);
; __device__ __forceinline__ void phase7(PP p, int wv) {
;     ...
;     for (int r = gw; r < NLAT; r += 2 * NGW) {
;         const int rb = r + NGW;
;         f32x4 va[4], vb[4]; u32x2 da[4], db[4];
;         row_load_nt(p->x + (size_t)r * D, lane, va); row_load_nt(p->x + (size_t)rb * D, lane, vb);
; #pragma unroll
;         for (int j = 0; j < 4; ++j) { da[j] = *(const u32x2*)(o1 + (size_t)r * D + 4 * lane + 256 * j); db[j] = *(const u32x2*)(o1 + (size_t)rb * D + 4 * lane + 256 * j); }
; #pragma unroll
;         for (int j = 0; j < 4; ++j) {
;             va[j][0] += bflo(da[j].x); va[j][1] += bfhi(da[j].x); va[j][2] += bflo(da[j].y); va[j][3] += bfhi(da[j].y);
;             vb[j][0] += bflo(db[j].x); vb[j][1] += bfhi(db[j].x); vb[j][2] += bflo(db[j].y); vb[j][3] += bfhi(db[j].y);
;         }
;         const float sa = row_rstd(va), sb = row_rstd(vb);
.LBB0_906:
	v_ashrrev_i32_e32 v57, 31, v56
	v_lshlrev_b64 v[52:53], 11, v[56:57]
	v_lshl_add_u64 v[54:55], v[40:41], 0, v[52:53]
	v_add_u32_e32 v52, s26, v56
	v_ashrrev_i32_e32 v53, 31, v52
	v_lshlrev_b64 v[58:59], 12, v[56:57]
	v_lshlrev_b64 v[62:63], 11, v[52:53]
	v_lshl_add_u64 v[80:81], v[38:39], 0, v[58:59]
	v_lshl_add_u64 v[82:83], v[40:41], 0, v[62:63]
	global_load_dwordx2 v[66:67], v[54:55], off
	global_load_dwordx2 v[76:77], v[54:55], off offset:512
	global_load_dwordx2 v[78:79], v[54:55], off offset:1024
	global_load_dwordx4 v[58:61], v[80:81], off nt
	v_lshlrev_b32_e32 v36, 2, v34
	global_load_dwordx2 v[54:55], v[54:55], off offset:1536
	s_nop 0
	global_load_dwordx2 v[90:91], v[82:83], off
	global_load_dwordx4 v[62:65], v[80:81], off offset:1024 nt
	global_load_dwordx2 v[92:93], v[82:83], off offset:512
	global_load_dwordx4 v[68:71], v[80:81], off offset:2048 nt
	global_load_dwordx2 v[98:99], v[82:83], off offset:1024
	global_load_dwordx4 v[72:75], v[80:81], off offset:3072 nt
	global_load_dwordx2 v[110:111], v[82:83], off offset:1536
	v_lshlrev_b64 v[80:81], 12, v[52:53]
	v_lshl_add_u64 v[80:81], v[38:39], 0, v[80:81]
	global_load_dwordx4 v[82:85], v[80:81], off nt
	global_load_dwordx4 v[94:97], v[80:81], off offset:1024 nt
	global_load_dwordx4 v[102:105], v[80:81], off offset:2048 nt
	global_load_dwordx4 v[106:109], v[80:81], off offset:3072 nt
	v_ashrrev_i32_e32 v53, 14, v56
	v_cmp_ne_u32_e32 vcc, v53, v101
	s_waitcnt vmcnt(15)
	v_lshlrev_b32_e32 v80, 16, v66
	v_and_b32_e32 v81, 0xffff0000, v66
	s_waitcnt vmcnt(14)
	v_lshlrev_b32_e32 v112, 16, v76
	v_and_b32_e32 v113, 0xffff0000, v76
	v_lshlrev_b32_e32 v66, 16, v67
	v_and_b32_e32 v67, 0xffff0000, v67
	v_lshlrev_b32_e32 v76, 16, v77
	v_and_b32_e32 v77, 0xffff0000, v77
	s_waitcnt vmcnt(13)
	v_lshlrev_b32_e32 v114, 16, v78
	v_and_b32_e32 v115, 0xffff0000, v78
	s_waitcnt vmcnt(11)
	v_lshlrev_b32_e32 v118, 16, v54
	v_and_b32_e32 v119, 0xffff0000, v54
	v_lshlrev_b32_e32 v54, 16, v55
	v_and_b32_e32 v55, 0xffff0000, v55
	v_pk_add_f32 v[86:87], v[58:59], v[80:81]
	s_waitcnt vmcnt(10)
	v_lshlrev_b32_e32 v58, 16, v90
	v_and_b32_e32 v59, 0xffff0000, v90
	s_waitcnt vmcnt(9)
	v_pk_add_f32 v[80:81], v[62:63], v[112:113]
	v_lshlrev_b32_e32 v116, 16, v79
	v_and_b32_e32 v117, 0xffff0000, v79
	v_pk_add_f32 v[88:89], v[60:61], v[66:67]
	v_lshlrev_b32_e32 v66, 16, v91
	v_and_b32_e32 v67, 0xffff0000, v91
	v_pk_add_f32 v[78:79], v[64:65], v[76:77]
	s_waitcnt vmcnt(8)
	v_lshlrev_b32_e32 v64, 16, v92
	v_and_b32_e32 v65, 0xffff0000, v92
	v_lshlrev_b32_e32 v76, 16, v93
	v_and_b32_e32 v77, 0xffff0000, v93
	s_waitcnt vmcnt(7)
	v_pk_add_f32 v[68:69], v[68:69], v[114:115]
	s_waitcnt vmcnt(6)
	v_lshlrev_b32_e32 v112, 16, v98
	v_and_b32_e32 v113, 0xffff0000, v98
	v_lshlrev_b32_e32 v98, 16, v99
	v_and_b32_e32 v99, 0xffff0000, v99
	s_waitcnt vmcnt(5)
	v_pk_add_f32 v[60:61], v[72:73], v[118:119]
	v_pk_add_f32 v[62:63], v[74:75], v[54:55]
	s_waitcnt vmcnt(4)
	v_lshlrev_b32_e32 v54, 16, v110
	v_and_b32_e32 v55, 0xffff0000, v110
	s_waitcnt vmcnt(3)
	v_pk_add_f32 v[90:91], v[82:83], v[58:59]
	v_mov_b32_e32 v58, v87
	v_mov_b32_e32 v59, v81
	v_lshlrev_b32_e32 v72, 16, v111
	v_and_b32_e32 v73, 0xffff0000, v111
	v_pk_add_f32 v[92:93], v[84:85], v[66:67]
	s_waitcnt vmcnt(2)
	v_pk_add_f32 v[84:85], v[94:95], v[64:65]
	v_pk_add_f32 v[82:83], v[96:97], v[76:77]
	s_waitcnt vmcnt(1)
	v_pk_add_f32 v[76:77], v[104:105], v[98:99]
	s_waitcnt vmcnt(0)
	v_pk_add_f32 v[64:65], v[106:107], v[54:55]
	v_mov_b32_e32 v54, v86
	v_mov_b32_e32 v55, v80
	v_mov_b32_e32 v98, v69
	v_pk_mul_f32 v[58:59], v[58:59], v[58:59]
	v_mov_b32_e32 v99, v61
	v_pk_add_f32 v[70:71], v[70:71], v[116:117]
	v_pk_add_f32 v[66:67], v[108:109], v[72:73]
	v_mov_b32_e32 v72, v88
	v_mov_b32_e32 v73, v78
	v_mov_b32_e32 v96, v68
	v_mov_b32_e32 v97, v60
	v_pk_fma_f32 v[54:55], v[54:55], v[54:55], v[58:59]
	v_pk_mul_f32 v[58:59], v[98:99], v[98:99]
	v_mov_b32_e32 v94, v89
	v_mov_b32_e32 v95, v79
	v_pk_fma_f32 v[54:55], v[72:73], v[72:73], v[54:55]
	v_pk_fma_f32 v[58:59], v[96:97], v[96:97], v[58:59]
	v_mov_b32_e32 v72, v70
	v_mov_b32_e32 v73, v62
	v_pk_fma_f32 v[54:55], v[94:95], v[94:95], v[54:55]
	v_pk_fma_f32 v[58:59], v[72:73], v[72:73], v[58:59]
	v_mov_b32_e32 v72, v71
	v_mov_b32_e32 v73, v63
	v_mov_b32_e32 v94, v91
	v_mov_b32_e32 v95, v85
	v_pk_fma_f32 v[58:59], v[72:73], v[72:73], v[58:59]
	v_mov_b32_e32 v72, v90
	v_mov_b32_e32 v73, v84
	v_pk_mul_f32 v[94:95], v[94:95], v[94:95]
	v_pk_add_f32 v[74:75], v[102:103], v[112:113]
	v_pk_fma_f32 v[72:73], v[72:73], v[72:73], v[94:95]
	v_mov_b32_e32 v94, v92
	v_mov_b32_e32 v95, v82
	v_pk_fma_f32 v[72:73], v[94:95], v[94:95], v[72:73]
	v_mov_b32_e32 v94, v93
	v_mov_b32_e32 v95, v83
	v_mov_b32_e32 v96, v75
	v_mov_b32_e32 v97, v65
	v_pk_fma_f32 v[72:73], v[94:95], v[94:95], v[72:73]
	v_mov_b32_e32 v94, v74
	v_mov_b32_e32 v95, v64
	v_pk_mul_f32 v[96:97], v[96:97], v[96:97]
	s_nop 0
	v_pk_fma_f32 v[94:95], v[94:95], v[94:95], v[96:97]
	v_mov_b32_e32 v96, v76
	v_mov_b32_e32 v97, v66
	v_pk_fma_f32 v[94:95], v[96:97], v[96:97], v[94:95]
	v_mov_b32_e32 v96, v77
	v_mov_b32_e32 v97, v67
	v_pk_fma_f32 v[94:95], v[96:97], v[96:97], v[94:95]
	v_mov_b32_e32 v96, v72
	v_mov_b32_e32 v97, v54
	v_mov_b32_e32 v54, v73
	v_pk_add_f32 v[54:55], v[96:97], v[54:55]
	v_mov_b32_e32 v72, v94
	v_mov_b32_e32 v73, v58
	v_pk_add_f32 v[54:55], v[54:55], v[72:73]
	v_mov_b32_e32 v58, v95
	v_pk_add_f32 v[54:55], v[54:55], v[58:59]
	v_lshlrev_b32_e32 v72, 2, v44
	s_waitcnt lgkmcnt(0)
	v_mov_b32_e32 v59, v55
	v_mov_b32_e32 v58, v54
	s_nop 1
	v_permlane32_swap_b32_e32 v55, v59
	v_permlane32_swap_b32_e32 v54, v58
	v_pk_add_f32 v[54:55], v[54:55], v[58:59]
	s_waitcnt lgkmcnt(0)
	v_mov_b32_e32 v59, v55
	v_mov_b32_e32 v58, v54
	s_nop 1
	v_permlane16_swap_b32_e32 v55, v59
	v_permlane16_swap_b32_e32 v54, v58
	v_pk_add_f32 v[54:55], v[54:55], v[58:59]
	s_waitcnt lgkmcnt(0)
	s_nop 1
	v_add_f32_dpp v54, v54, v54 row_ror:8 row_mask:0xf bank_mask:0xf
	v_add_f32_dpp v55, v55, v55 row_ror:8 row_mask:0xf bank_mask:0xf
	s_waitcnt lgkmcnt(0)
	s_nop 1
	v_add_f32_dpp v54, v54, v54 row_ror:4 row_mask:0xf bank_mask:0xf
	v_add_f32_dpp v55, v55, v55 row_ror:4 row_mask:0xf bank_mask:0xf
	s_waitcnt lgkmcnt(0)
	s_nop 1
	v_add_f32_dpp v94, v54, v54 quad_perm:[2,3,0,1] row_mask:0xf bank_mask:0xf
	v_add_f32_dpp v95, v55, v55 quad_perm:[2,3,0,1] row_mask:0xf bank_mask:0xf
	ds_bpermute_b32 v97, v100, v95
	ds_bpermute_b32 v96, v100, v94
	v_lshlrev_b32_e32 v58, 2, v46
	v_lshlrev_b32_e32 v54, 2, v48
	s_and_saveexec_b64 s[4:5], vcc
	s_cbranch_execz .LBB0_908
; __device__ __forceinline__ void phase7(PP p, int wv) {
;     ...
;         const int ma = r >> 14;
;         if (ma != cur) {
;             cur = ma;
; #pragma unroll
;             for (int j = 0; j < 4; ++j) {
;                 const int c = 4 * lane + 256 * j;
;                 gsc[j] = *(const f32x4*)(p->norm2_g + c) * (*(const f32x4*)(mod + ma * 6144 + 4096 + c) + 1.0f);
;                 gsh[j] = *(const f32x4*)(mod + ma * 6144 + 3072 + c);
;             }
;         }
	v_mul_i32_i24_e32 v0, 0x1800, v53
	v_ashrrev_i32_e32 v1, 31, v0
	v_lshl_add_u64 v[0:1], v[0:1], 2, s[14:15]
	v_lshl_add_u64 v[2:3], v[0:1], 0, s[18:19]
	s_load_dwordx2 s[28:29], s[6:7], 0x98
	v_lshl_add_u64 v[12:13], v[0:1], 0, s[20:21]
	v_lshl_add_u64 v[0:1], v[2:3], 0, v[36:37]
	v_mov_b32_e32 v73, v37
	global_load_dwordx4 v[16:19], v[0:1], off
	v_lshl_add_u64 v[0:1], v[2:3], 0, v[72:73]
	v_mov_b32_e32 v59, v37
	global_load_dwordx4 v[20:23], v[0:1], off
	v_lshl_add_u64 v[0:1], v[2:3], 0, v[58:59]
	v_mov_b32_e32 v55, v37
	v_lshl_add_u64 v[4:5], v[12:13], 0, v[36:37]
	global_load_dwordx4 v[24:27], v[0:1], off
	v_lshl_add_u64 v[6:7], v[2:3], 0, v[54:55]
	v_lshl_add_u64 v[8:9], v[12:13], 0, v[72:73]
	global_load_dwordx4 v[28:31], v[6:7], off
	global_load_dwordx4 v[0:3], v[4:5], off
	s_waitcnt lgkmcnt(0)
	global_load_dwordx4 v[102:105], v36, s[28:29]
	global_load_dwordx4 v[106:109], v36, s[28:29] offset:1024
	global_load_dwordx4 v[4:7], v[8:9], off
	global_load_dwordx4 v[110:113], v36, s[28:29] offset:2048
	v_lshl_add_u64 v[14:15], v[12:13], 0, v[58:59]
	v_lshl_add_u64 v[12:13], v[12:13], 0, v[54:55]
	global_load_dwordx4 v[114:117], v36, s[28:29] offset:3072
	global_load_dwordx4 v[8:11], v[14:15], off
	v_mov_b32_e32 v101, v53
	global_load_dwordx4 v[12:15], v[12:13], off
	s_waitcnt vmcnt(11)
	v_pk_add_f32 v[18:19], v[18:19], 1.0 op_sel_hi:[1,0]
	v_pk_add_f32 v[16:17], v[16:17], 1.0 op_sel_hi:[1,0]
	s_waitcnt vmcnt(10)
	v_pk_add_f32 v[22:23], v[22:23], 1.0 op_sel_hi:[1,0]
	v_pk_add_f32 v[20:21], v[20:21], 1.0 op_sel_hi:[1,0]
	s_waitcnt vmcnt(9)
	v_pk_add_f32 v[26:27], v[26:27], 1.0 op_sel_hi:[1,0]
	v_pk_add_f32 v[24:25], v[24:25], 1.0 op_sel_hi:[1,0]
	s_waitcnt vmcnt(8)
	v_pk_add_f32 v[30:31], v[30:31], 1.0 op_sel_hi:[1,0]
	v_pk_add_f32 v[28:29], v[28:29], 1.0 op_sel_hi:[1,0]
	s_waitcnt vmcnt(6)
	v_pk_mul_f32 v[18:19], v[104:105], v[18:19]
	v_pk_mul_f32 v[16:17], v[102:103], v[16:17]
	s_waitcnt vmcnt(5)
	v_pk_mul_f32 v[22:23], v[108:109], v[22:23]
	v_pk_mul_f32 v[20:21], v[106:107], v[20:21]
	s_waitcnt vmcnt(3)
	v_pk_mul_f32 v[26:27], v[112:113], v[26:27]
	v_pk_mul_f32 v[24:25], v[110:111], v[24:25]
	s_waitcnt vmcnt(2)
	v_pk_mul_f32 v[30:31], v[116:117], v[30:31]
	v_pk_mul_f32 v[28:29], v[114:115], v[28:29]

; __device__ __forceinline__ float bflo(unsigned w) { return __uint_as_float(w << 16); }
; __device__ __forceinline__ float bfhi(unsigned w) { return __uint_as_float(w & 0xFFFF0000u); }
; __device__ __forceinline__ void final_phase(PP p, int wv) {
;     ...
;     for (int r = gw; r < NLAT; r += 2 * NGW) {
;         const int rb = r + NGW;
;         f32x4 va[4], vb[4]; u32x2 da[4], db[4], ea[4], eb[4];
;         row_load_nt(p->x + (size_t)r * D, lane, va); row_load_nt(p->x + (size_t)rb * D, lane, vb);
; #pragma unroll
;         for (int j = 0; j < 4; ++j) {
;             da[j] = *(const u32x2*)(o1 + (size_t)r * D + 4 * lane + 256 * j); db[j] = *(const u32x2*)(o1 + (size_t)rb * D + 4 * lane + 256 * j);
;             ea[j] = *(const u32x2*)(o2 + (size_t)r * D + 4 * lane + 256 * j); eb[j] = *(const u32x2*)(o2 + (size_t)rb * D + 4 * lane + 256 * j);
;         }
; #pragma unroll
;         for (int j = 0; j < 4; ++j) {
;             va[j][0] += bflo(da[j].x) + bflo(ea[j].x); va[j][1] += bfhi(da[j].x) + bfhi(ea[j].x); va[j][2] += bflo(da[j].y) + bflo(ea[j].y); va[j][3] += bfhi(da[j].y) + bfhi(ea[j].y);
;             vb[j][0] += bflo(db[j].x) + bflo(eb[j].x); vb[j][1] += bfhi(db[j].x) + bfhi(eb[j].x); vb[j][2] += bflo(db[j].y) + bflo(eb[j].y); vb[j][3] += bfhi(db[j].y) + bfhi(eb[j].y);
;         }
.LBB0_1181:
	v_ashrrev_i32_e32 v33, 31, v32
	v_add_u32_e32 v26, s26, v32
	v_lshlrev_b64 v[30:31], 11, v[32:33]
	v_lshlrev_b64 v[28:29], 12, v[32:33]
	v_ashrrev_i32_e32 v27, 31, v26
	v_lshl_add_u64 v[56:57], v[18:19], 0, v[30:31]
	v_add_u32_e32 v32, s26, v26
	v_lshl_add_u64 v[52:53], v[16:17], 0, v[28:29]
	v_lshlrev_b64 v[54:55], 12, v[26:27]
	v_lshlrev_b64 v[58:59], 11, v[26:27]
	v_lshl_add_u64 v[60:61], v[20:21], 0, v[30:31]
	v_lshl_add_u64 v[26:27], v[22:23], 0, v[28:29]
	global_load_dwordx2 v[68:69], v[56:57], off
	global_load_dwordx2 v[70:71], v[60:61], off
	global_load_dwordx2 v[72:73], v[56:57], off offset:512
	global_load_dwordx2 v[74:75], v[60:61], off offset:512
	global_load_dwordx2 v[76:77], v[56:57], off offset:1024
	global_load_dwordx2 v[78:79], v[60:61], off offset:1024
	global_load_dwordx2 v[80:81], v[56:57], off offset:1536
	global_load_dwordx4 v[28:31], v[52:53], off nt
	global_load_dwordx4 v[40:43], v[52:53], off offset:1024 nt
	global_load_dwordx2 v[82:83], v[60:61], off offset:1536
	global_load_dwordx4 v[44:47], v[52:53], off offset:2048 nt
	global_load_dwordx4 v[48:51], v[52:53], off offset:3072 nt
	v_lshl_add_u64 v[86:87], v[18:19], 0, v[58:59]
	v_lshl_add_u64 v[84:85], v[16:17], 0, v[54:55]
	v_lshl_add_u64 v[88:89], v[20:21], 0, v[58:59]
	v_lshl_add_u64 v[90:91], v[22:23], 0, v[54:55]
	global_load_dwordx2 v[92:93], v[86:87], off
	global_load_dwordx2 v[94:95], v[88:89], off
	global_load_dwordx2 v[96:97], v[86:87], off offset:512
	global_load_dwordx2 v[98:99], v[88:89], off offset:512
	global_load_dwordx2 v[100:101], v[86:87], off offset:1024
	global_load_dwordx2 v[102:103], v[88:89], off offset:1024
	global_load_dwordx2 v[104:105], v[86:87], off offset:1536
	global_load_dwordx2 v[106:107], v[88:89], off offset:1536
	global_load_dwordx4 v[52:55], v[84:85], off nt
	global_load_dwordx4 v[56:59], v[84:85], off offset:1024 nt
	global_load_dwordx4 v[60:63], v[84:85], off offset:2048 nt
	global_load_dwordx4 v[64:67], v[84:85], off offset:3072 nt
	v_cmp_lt_i32_e32 vcc, s6, v32
	s_or_b64 s[2:3], vcc, s[2:3]
	s_waitcnt vmcnt(23)
	v_lshlrev_b32_e32 v84, 16, v68
	v_and_b32_e32 v85, 0xffff0000, v68
	s_waitcnt vmcnt(22)
	v_lshlrev_b32_e32 v86, 16, v70
	v_and_b32_e32 v87, 0xffff0000, v70
	v_lshlrev_b32_e32 v68, 16, v69
	v_and_b32_e32 v69, 0xffff0000, v69
	v_lshlrev_b32_e32 v70, 16, v71
	v_and_b32_e32 v71, 0xffff0000, v71
	s_waitcnt vmcnt(21)
	v_lshlrev_b32_e32 v88, 16, v72
	v_and_b32_e32 v89, 0xffff0000, v72
	s_waitcnt vmcnt(20)
	v_lshlrev_b32_e32 v108, 16, v74
	v_and_b32_e32 v109, 0xffff0000, v74
	v_lshlrev_b32_e32 v72, 16, v73
	v_and_b32_e32 v73, 0xffff0000, v73
	v_lshlrev_b32_e32 v74, 16, v75
	v_and_b32_e32 v75, 0xffff0000, v75
	s_waitcnt vmcnt(19)
	v_lshlrev_b32_e32 v110, 16, v76
	v_and_b32_e32 v111, 0xffff0000, v76
	s_waitcnt vmcnt(18)
	v_lshlrev_b32_e32 v112, 16, v78
	v_and_b32_e32 v113, 0xffff0000, v78
	v_lshlrev_b32_e32 v76, 16, v77
	v_and_b32_e32 v77, 0xffff0000, v77
	v_lshlrev_b32_e32 v78, 16, v79
	v_and_b32_e32 v79, 0xffff0000, v79
	s_waitcnt vmcnt(17)
	v_lshlrev_b32_e32 v114, 16, v80
	v_and_b32_e32 v115, 0xffff0000, v80
	s_waitcnt vmcnt(14)
	v_lshlrev_b32_e32 v116, 16, v82
	v_and_b32_e32 v117, 0xffff0000, v82
	v_lshlrev_b32_e32 v80, 16, v81
	v_and_b32_e32 v81, 0xffff0000, v81
	v_lshlrev_b32_e32 v82, 16, v83
	v_and_b32_e32 v83, 0xffff0000, v83
	v_pk_add_f32 v[84:85], v[84:85], v[86:87]
	v_pk_add_f32 v[68:69], v[68:69], v[70:71]
	s_waitcnt vmcnt(11)
	v_lshlrev_b32_e32 v70, 16, v92
	v_and_b32_e32 v71, 0xffff0000, v92
	s_waitcnt vmcnt(10)
	v_lshlrev_b32_e32 v86, 16, v94
	v_and_b32_e32 v87, 0xffff0000, v94
	v_lshlrev_b32_e32 v92, 16, v93
	v_and_b32_e32 v93, 0xffff0000, v93
	v_lshlrev_b32_e32 v94, 16, v95
	v_and_b32_e32 v95, 0xffff0000, v95
	v_pk_add_f32 v[88:89], v[88:89], v[108:109]
	v_pk_add_f32 v[72:73], v[72:73], v[74:75]
	s_waitcnt vmcnt(9)
	v_lshlrev_b32_e32 v74, 16, v96
	v_and_b32_e32 v75, 0xffff0000, v96
	s_waitcnt vmcnt(8)
	v_lshlrev_b32_e32 v108, 16, v98
	v_and_b32_e32 v109, 0xffff0000, v98
	v_pk_add_f32 v[110:111], v[110:111], v[112:113]
	v_pk_add_f32 v[76:77], v[76:77], v[78:79]
	s_waitcnt vmcnt(7)
	v_lshlrev_b32_e32 v78, 16, v100
	v_and_b32_e32 v79, 0xffff0000, v100
	s_waitcnt vmcnt(6)
	v_lshlrev_b32_e32 v112, 16, v102
	v_and_b32_e32 v113, 0xffff0000, v102
	v_lshlrev_b32_e32 v100, 16, v101
	v_and_b32_e32 v101, 0xffff0000, v101
	v_lshlrev_b32_e32 v102, 16, v103
	v_and_b32_e32 v103, 0xffff0000, v103
	v_pk_add_f32 v[114:115], v[114:115], v[116:117]
	v_pk_add_f32 v[80:81], v[80:81], v[82:83]
	s_waitcnt vmcnt(5)
	v_lshlrev_b32_e32 v82, 16, v104
	v_and_b32_e32 v83, 0xffff0000, v104
	s_waitcnt vmcnt(4)
	v_lshlrev_b32_e32 v116, 16, v106
	v_and_b32_e32 v117, 0xffff0000, v106
	v_pk_add_f32 v[28:29], v[28:29], v[84:85]
	v_pk_add_f32 v[30:31], v[30:31], v[68:69]
	v_pk_add_f32 v[68:69], v[70:71], v[86:87]
	v_pk_add_f32 v[70:71], v[92:93], v[94:95]
	v_pk_add_f32 v[40:41], v[40:41], v[88:89]
	v_pk_add_f32 v[42:43], v[42:43], v[72:73]
	v_pk_add_f32 v[72:73], v[74:75], v[108:109]
	v_pk_add_f32 v[44:45], v[44:45], v[110:111]
	v_pk_add_f32 v[46:47], v[46:47], v[76:77]
	v_pk_add_f32 v[76:77], v[78:79], v[112:113]
	v_pk_add_f32 v[78:79], v[100:101], v[102:103]
	v_pk_add_f32 v[48:49], v[48:49], v[114:115]
	v_lshlrev_b32_e32 v96, 16, v97
	v_and_b32_e32 v97, 0xffff0000, v97
	v_lshlrev_b32_e32 v98, 16, v99
	v_and_b32_e32 v99, 0xffff0000, v99
	v_pk_add_f32 v[50:51], v[50:51], v[80:81]
	v_pk_add_f32 v[80:81], v[82:83], v[116:117]
	s_waitcnt vmcnt(3)
	v_pk_add_f32 v[52:53], v[52:53], v[68:69]
	v_pk_add_f32 v[54:55], v[54:55], v[70:71]
	s_waitcnt vmcnt(2)
	v_pk_add_f32 v[56:57], v[56:57], v[72:73]
	s_waitcnt vmcnt(1)
; __device__ __forceinline__ float bflo(unsigned w) { return __uint_as_float(w << 16); }
; __device__ __forceinline__ float bfhi(unsigned w) { return __uint_as_float(w & 0xFFFF0000u); }
; __device__ __forceinline__ float row_rstd(const f32x4 (&v)[4]) {
;     float ss = 0.f;
; #pragma unroll
;     for (int j = 0; j < 4; ++j) ss += v[j][0] * v[j][0] + v[j][1] * v[j][1] + v[j][2] * v[j][2] + v[j][3] * v[j][3];
;     return rsqrtf(wave_sum(ss) * (1.0f / D) + EPS);
; __device__ __forceinline__ void final_phase(PP p, int wv) {
;     ...
; #pragma unroll
;         for (int j = 0; j < 4; ++j) {
;             va[j][0] += bflo(da[j].x) + bflo(ea[j].x); va[j][1] += bfhi(da[j].x) + bfhi(ea[j].x); va[j][2] += bflo(da[j].y) + bflo(ea[j].y); va[j][3] += bfhi(da[j].y) + bfhi(ea[j].y);
;             vb[j][0] += bflo(db[j].x) + bflo(eb[j].x); vb[j][1] += bfhi(db[j].x) + bfhi(eb[j].x); vb[j][2] += bflo(db[j].y) + bflo(eb[j].y); vb[j][3] += bfhi(db[j].y) + bfhi(eb[j].y);
;         }
;         const float sa = row_rstd(va), sb = row_rstd(vb);
;         float* rowa = p->out + (size_t)r * D; float* rowb = p->out + (size_t)rb * D;
; #pragma unroll
;         for (int j = 0; j < 4; ++j) { const f32x4 gg = fg[j]; *(f32x4*)(rowa + 4 * lane + 256 * j) = va[j] * sa * gg; *(f32x4*)(rowb + 4 * lane + 256 * j) = vb[j] * sb * gg; }
;     }
	v_pk_add_f32 v[62:63], v[62:63], v[78:79]
	v_mov_b32_e32 v70, v29
	v_mov_b32_e32 v71, v41
	v_mov_b32_e32 v78, v45
	v_mov_b32_e32 v79, v49
	v_lshlrev_b32_e32 v104, 16, v105
	v_and_b32_e32 v105, 0xffff0000, v105
	v_lshlrev_b32_e32 v106, 16, v107
	v_and_b32_e32 v107, 0xffff0000, v107
	v_pk_add_f32 v[74:75], v[96:97], v[98:99]
	v_pk_add_f32 v[60:61], v[60:61], v[76:77]
	s_waitcnt vmcnt(0)
	v_pk_add_f32 v[64:65], v[64:65], v[80:81]
	v_mov_b32_e32 v68, v28
	v_mov_b32_e32 v69, v40
	v_mov_b32_e32 v76, v44
	v_mov_b32_e32 v77, v48
	v_pk_mul_f32 v[70:71], v[70:71], v[70:71]
	v_pk_mul_f32 v[78:79], v[78:79], v[78:79]
	v_mov_b32_e32 v86, v53
	v_mov_b32_e32 v87, v57
	v_pk_add_f32 v[82:83], v[104:105], v[106:107]
	v_pk_add_f32 v[58:59], v[58:59], v[74:75]
	v_mov_b32_e32 v72, v30
	v_mov_b32_e32 v73, v42
	v_mov_b32_e32 v84, v52
	v_mov_b32_e32 v85, v56
	v_mov_b32_e32 v96, v61
	v_mov_b32_e32 v97, v65
	v_pk_fma_f32 v[68:69], v[68:69], v[68:69], v[70:71]
	v_pk_fma_f32 v[70:71], v[76:77], v[76:77], v[78:79]
	v_pk_mul_f32 v[76:77], v[86:87], v[86:87]
	v_pk_add_f32 v[66:67], v[66:67], v[82:83]
	v_mov_b32_e32 v88, v54
	v_mov_b32_e32 v89, v58
	v_mov_b32_e32 v94, v60
	v_mov_b32_e32 v95, v64
	v_pk_mul_f32 v[78:79], v[96:97], v[96:97]
	v_pk_fma_f32 v[68:69], v[72:73], v[72:73], v[68:69]
	v_pk_fma_f32 v[72:73], v[84:85], v[84:85], v[76:77]
	v_mov_b32_e32 v74, v31
	v_mov_b32_e32 v75, v43
	v_mov_b32_e32 v80, v46
	v_mov_b32_e32 v81, v50
	v_mov_b32_e32 v92, v55
	v_mov_b32_e32 v93, v59
	v_mov_b32_e32 v98, v62
	v_mov_b32_e32 v99, v66
	v_pk_fma_f32 v[76:77], v[94:95], v[94:95], v[78:79]
	v_pk_fma_f32 v[72:73], v[88:89], v[88:89], v[72:73]
	v_mov_b32_e32 v82, v47
	v_mov_b32_e32 v83, v51
	v_mov_b32_e32 v100, v63
	v_mov_b32_e32 v101, v67
	v_pk_fma_f32 v[70:71], v[80:81], v[80:81], v[70:71]
	v_pk_fma_f32 v[68:69], v[74:75], v[74:75], v[68:69]
	v_pk_fma_f32 v[74:75], v[98:99], v[98:99], v[76:77]
	v_pk_fma_f32 v[72:73], v[92:93], v[92:93], v[72:73]
	v_pk_fma_f32 v[70:71], v[82:83], v[82:83], v[70:71]
	v_pk_fma_f32 v[74:75], v[100:101], v[100:101], v[74:75]
	v_mov_b32_e32 v77, v68
	v_mov_b32_e32 v76, v72
	v_mov_b32_e32 v68, v73
	v_mov_b32_e32 v79, v70
	v_mov_b32_e32 v78, v74
	v_pk_add_f32 v[68:69], v[76:77], v[68:69]
	v_mov_b32_e32 v70, v75
	v_pk_add_f32 v[68:69], v[68:69], v[78:79]
	s_nop 0
	v_pk_add_f32 v[68:69], v[68:69], v[70:71]
	s_waitcnt lgkmcnt(0)
	v_mov_b32_e32 v71, v69
	v_mov_b32_e32 v70, v68
	s_nop 1
	v_permlane32_swap_b32_e32 v69, v71
	v_permlane32_swap_b32_e32 v68, v70
	v_pk_add_f32 v[68:69], v[68:69], v[70:71]
	s_waitcnt lgkmcnt(0)
	v_mov_b32_e32 v71, v69
	v_mov_b32_e32 v70, v68
	s_nop 1
	v_permlane16_swap_b32_e32 v69, v71
	v_permlane16_swap_b32_e32 v68, v70
	v_pk_add_f32 v[68:69], v[68:69], v[70:71]
	s_waitcnt lgkmcnt(0)
	s_nop 1
	v_add_f32_dpp v68, v68, v68 row_ror:8 row_mask:0xf bank_mask:0xf
	v_add_f32_dpp v69, v69, v69 row_ror:8 row_mask:0xf bank_mask:0xf
	s_waitcnt lgkmcnt(0)
	s_nop 1
	v_add_f32_dpp v68, v68, v68 row_ror:4 row_mask:0xf bank_mask:0xf
	v_add_f32_dpp v69, v69, v69 row_ror:4 row_mask:0xf bank_mask:0xf
	s_waitcnt lgkmcnt(0)
	s_nop 1
	v_add_f32_dpp v68, v68, v68 quad_perm:[2,3,0,1] row_mask:0xf bank_mask:0xf
	v_add_f32_dpp v69, v69, v69 quad_perm:[2,3,0,1] row_mask:0xf bank_mask:0xf
	s_waitcnt lgkmcnt(0)
	s_nop 1
	v_add_f32_dpp v68, v68, v68 quad_perm:[1,0,3,2] row_mask:0xf bank_mask:0xf
	v_add_f32_dpp v69, v69, v69 quad_perm:[1,0,3,2] row_mask:0xf bank_mask:0xf
	s_nop 0
	v_pk_fma_f32 v[68:69], v[68:69], s[4:5], v[24:25] op_sel_hi:[1,0,0]
	s_nop 0
	v_mul_f32_e32 v33, 0x4b800000, v69
	v_cmp_gt_f32_e64 s[0:1], s5, v69
	v_mul_f32_e32 v39, 0x4b800000, v68
	v_cmp_gt_f32_e32 vcc, s5, v68
	v_cndmask_b32_e64 v33, v69, v33, s[0:1]
	v_rsq_f32_e32 v33, v33
	v_cndmask_b32_e32 v39, v68, v39, vcc
	v_rsq_f32_e32 v39, v39
	v_mul_f32_e32 v68, 0x45800000, v33
	v_cndmask_b32_e64 v68, v33, v68, s[0:1]
	v_mul_f32_e32 v69, 0x45800000, v39
	v_cndmask_b32_e32 v70, v39, v69, vcc
	v_pk_mul_f32 v[28:29], v[28:29], v[68:69] op_sel_hi:[1,0]
	v_pk_mul_f32 v[30:31], v[30:31], v[68:69] op_sel_hi:[1,0]
	v_pk_mul_f32 v[52:53], v[52:53], v[70:71] op_sel_hi:[1,0]
	v_pk_mul_f32 v[54:55], v[54:55], v[70:71] op_sel_hi:[1,0]
	v_pk_mul_f32 v[72:73], v[40:41], v[68:69] op_sel_hi:[1,0]
	v_pk_mul_f32 v[74:75], v[42:43], v[68:69] op_sel_hi:[1,0]
	v_pk_mul_f32 v[56:57], v[56:57], v[70:71] op_sel_hi:[1,0]
	v_pk_mul_f32 v[58:59], v[58:59], v[70:71] op_sel_hi:[1,0]
	v_pk_mul_f32 v[76:77], v[44:45], v[68:69] op_sel_hi:[1,0]
	v_pk_mul_f32 v[78:79], v[46:47], v[68:69] op_sel_hi:[1,0]
	v_pk_mul_f32 v[60:61], v[60:61], v[70:71] op_sel_hi:[1,0]
	v_pk_mul_f32 v[62:63], v[62:63], v[70:71] op_sel_hi:[1,0]
	v_pk_mul_f32 v[80:81], v[48:49], v[68:69] op_sel_hi:[1,0]
	v_pk_mul_f32 v[68:69], v[50:51], v[68:69] op_sel_hi:[1,0]
	v_pk_mul_f32 v[64:65], v[64:65], v[70:71] op_sel_hi:[1,0]
	v_pk_mul_f32 v[66:67], v[66:67], v[70:71] op_sel_hi:[1,0]
	v_pk_mul_f32 v[30:31], v[2:3], v[30:31]
	v_pk_mul_f32 v[28:29], v[0:1], v[28:29]
	v_pk_mul_f32 v[42:43], v[2:3], v[54:55]
	v_pk_mul_f32 v[40:41], v[0:1], v[52:53]
	v_pk_mul_f32 v[46:47], v[6:7], v[74:75]
	v_pk_mul_f32 v[44:45], v[4:5], v[72:73]
	v_pk_mul_f32 v[50:51], v[6:7], v[58:59]
	v_pk_mul_f32 v[48:49], v[4:5], v[56:57]
	v_pk_mul_f32 v[54:55], v[10:11], v[78:79]
	v_pk_mul_f32 v[52:53], v[8:9], v[76:77]
	v_pk_mul_f32 v[58:59], v[10:11], v[62:63]
	v_pk_mul_f32 v[56:57], v[8:9], v[60:61]
	v_pk_mul_f32 v[62:63], v[14:15], v[68:69]
	v_pk_mul_f32 v[60:61], v[12:13], v[80:81]
	v_pk_mul_f32 v[66:67], v[14:15], v[66:67]
	v_pk_mul_f32 v[64:65], v[12:13], v[64:65]
	global_store_dwordx4 v[26:27], v[28:31], off
	global_store_dwordx4 v[90:91], v[40:43], off
	global_store_dwordx4 v[26:27], v[44:47], off offset:1024
	global_store_dwordx4 v[90:91], v[48:51], off offset:1024
	global_store_dwordx4 v[26:27], v[52:55], off offset:2048
	global_store_dwordx4 v[90:91], v[56:59], off offset:2048
	global_store_dwordx4 v[26:27], v[60:63], off offset:3072
	global_store_dwordx4 v[90:91], v[64:67], off offset:3072
	s_andn2_b64 exec, exec, s[2:3]
	s_cbranch_execnz .LBB0_1181
